# FoX sample-attention cache loads use default cache policy instead of nt (on top of v12)
# baseline (speedup 1.0000x reference)
.LBB0_642:
	s_or_b64 exec, exec, s[0:1]
	s_add_i32 s21, 0, 0x1e000
	v_mov_b32_e32 v10, s21
	v_mad_u64_u32 v[10:11], s[0:1], v1, 20, v[10:11]
	v_pk_add_f32 v[2:3], v[2:3], v[8:9] op_sel_hi:[1,0]
	s_mov_b32 s0, 0x3fb8aa3b
	v_pk_mul_f32 v[2:3], v[2:3], s[0:1] op_sel_hi:[1,0]
	ds_write2_b32 v10, v2, v3 offset1:1
	v_pk_add_f32 v[2:3], v[6:7], v[8:9] op_sel_hi:[1,0]
	s_and_b32 s20, s26, 15
	v_pk_mul_f32 v[2:3], v[2:3], s[0:1] op_sel_hi:[1,0]
	s_lshl_b64 s[18:19], s[16:17], 11
	s_lshl_b64 s[0:1], s[16:17], 12
	s_add_u32 s0, s28, s0
	v_readlane_b32 s24, v254, 28
	v_add_f32_e32 v1, v5, v8
	s_addc_u32 s1, s29, s1
	s_lshl_b32 s2, s24, 7
	s_lshl_b32 s3, s24, 8
	v_mul_f32_e32 v1, 0x3fb8aa3b, v1
	s_add_u32 s22, s0, s3
	v_mov_b32_e32 v145, v0
	ds_write2_b32 v10, v2, v3 offset0:2 offset1:3
	ds_write_b32 v10, v1 offset:16
	s_waitcnt lgkmcnt(0)
	s_barrier
	s_addc_u32 s23, s1, 0
	s_lshl_b64 s[0:1], s[14:15], 15
	s_add_u32 s0, s0, s10
	v_and_b32_e32 v1, 15, v145
	v_bfe_u32 v121, v145, 4, 2
	v_lshlrev_b32_e32 v2, 12, v1
	v_mov_b32_e32 v3, v4
	v_readlane_b32 s25, v254, 29
	s_addc_u32 s1, s1, s11
	v_lshl_add_u64 v[2:3], s[22:23], 0, v[2:3]
	v_lshlrev_b32_e32 v124, 4, v121
	v_mov_b32_e32 v125, v4
	s_or_b64 s[24:25], s[0:1], s[24:25]
	v_readlane_b32 s48, v253, 35
	v_lshl_add_u64 v[2:3], v[2:3], 0, v[124:125]
	s_lshl_b64 s[24:25], s[24:25], 9
	v_readlane_b32 s52, v253, 39
	global_load_dwordx4 v[18:21], v[2:3], off
	global_load_dwordx4 v[14:17], v[2:3], off offset:64
	global_load_dwordx4 v[10:13], v[2:3], off offset:128
	global_load_dwordx4 v[6:9], v[2:3], off offset:192
	v_bfe_u32 v2, v145, 1, 1
	v_and_b32_e32 v146, 12, v145
	v_ashrrev_i32_e32 v122, 5, v145
	v_readlane_b32 s49, v253, 36
	v_readlane_b32 s53, v253, 40
	s_add_u32 s48, s52, s24
	v_bitop3_b32 v2, v121, v2, v146 bitop3:0x36
	v_ashrrev_i32_e32 v123, 31, v122
	v_readlane_b32 s54, v253, 41
	s_addc_u32 s49, s53, s25
	v_lshlrev_b32_e32 v29, 4, v2
	v_lshlrev_b32_e32 v2, 3, v145
	v_and_b32_e32 v22, 31, v145
	v_lshlrev_b64 v[118:119], 13, v[122:123]
	v_readlane_b32 s55, v253, 42
	s_add_u32 s24, s54, s24
	v_and_b32_e32 v30, 8, v2
	v_lshl_add_u64 v[2:3], s[48:49], 0, v[118:119]
	v_lshlrev_b32_e32 v120, 2, v22
	v_lshlrev_b32_e32 v22, 4, v22
	v_mov_b32_e32 v23, v4
	s_addc_u32 s25, s55, s25
	v_lshl_add_u64 v[2:3], v[2:3], 0, v[22:23]
	v_lshlrev_b32_e32 v26, 2, v122
	v_lshl_add_u64 v[24:25], s[24:25], 0, v[118:119]
	v_and_b32_e32 v33, 12, v26
	v_add_co_u32_e32 v26, vcc, s94, v2
	v_lshl_add_u64 v[24:25], v[24:25], 0, v[22:23]
	s_nop 0
	v_addc_co_u32_e32 v27, vcc, 0, v3, vcc
	global_load_dwordx4 v[114:117], v[2:3], off
	global_load_dwordx4 v[110:113], v[24:25], off
	global_load_dwordx4 v[106:109], v[26:27], off
	v_add_co_u32_e32 v26, vcc, s94, v24
	s_mov_b32 s23, 0x40000
	s_nop 0
	v_addc_co_u32_e32 v27, vcc, 0, v25, vcc
	global_load_dwordx4 v[102:105], v[26:27], off
	v_add_co_u32_e32 v26, vcc, s23, v2
	s_mov_b32 s48, 0xc0000
	s_nop 0
	v_addc_co_u32_e32 v27, vcc, 0, v3, vcc
	global_load_dwordx4 v[98:101], v[26:27], off
	v_add_co_u32_e32 v26, vcc, s23, v24
	s_mov_b32 s23, 0x60000
	s_nop 0
	v_addc_co_u32_e32 v27, vcc, 0, v25, vcc
	global_load_dwordx4 v[94:97], v[26:27], off
	v_add_co_u32_e32 v26, vcc, s23, v2
	v_readfirstlane_b32 s33, v145
	s_nop 0
	v_addc_co_u32_e32 v27, vcc, 0, v3, vcc
	global_load_dwordx4 v[90:93], v[26:27], off
	v_add_co_u32_e32 v26, vcc, s23, v24
	s_mov_b32 s23, 0x80000
	s_nop 0
	v_addc_co_u32_e32 v27, vcc, 0, v25, vcc
	global_load_dwordx4 v[82:85], v[26:27], off
	v_add_co_u32_e32 v26, vcc, s23, v2
	s_ashr_i32 s15, s33, 6
	s_nop 0
	v_addc_co_u32_e32 v27, vcc, 0, v3, vcc
	global_load_dwordx4 v[74:77], v[26:27], off
	v_add_co_u32_e32 v26, vcc, s23, v24
	s_mov_b32 s23, 0xa0000
	s_nop 0
	v_addc_co_u32_e32 v27, vcc, 0, v25, vcc
	global_load_dwordx4 v[66:69], v[26:27], off
	v_add_co_u32_e32 v26, vcc, s23, v2
	s_andn2_b32 s33, s33, 63
	s_nop 0
	v_addc_co_u32_e32 v27, vcc, 0, v3, vcc
	global_load_dwordx4 v[54:57], v[26:27], off
	v_add_co_u32_e32 v26, vcc, s23, v24
	s_mov_b32 s23, 0xe0000
	s_nop 0
	v_addc_co_u32_e32 v27, vcc, 0, v25, vcc
	global_load_dwordx4 v[86:89], v[26:27], off
	v_add_co_u32_e32 v26, vcc, s48, v2
	s_lshl_b32 s22, s15, 4
	s_nop 0
	v_addc_co_u32_e32 v27, vcc, 0, v3, vcc
	global_load_dwordx4 v[78:81], v[26:27], off
	v_add_co_u32_e32 v26, vcc, s48, v24
	v_bfe_u32 v28, v145, 2, 2
	s_nop 0
	v_addc_co_u32_e32 v27, vcc, 0, v25, vcc
	v_add_co_u32_e32 v2, vcc, s23, v2
	global_load_dwordx4 v[70:73], v[26:27], off
	s_nop 0
	v_addc_co_u32_e32 v3, vcc, 0, v3, vcc
	global_load_dwordx4 v[62:65], v[2:3], off
	v_add_co_u32_e32 v2, vcc, s23, v24
	v_lshlrev_b32_e32 v125, 2, v121
	s_nop 0
	v_addc_co_u32_e32 v3, vcc, 0, v25, vcc
	global_load_dwordx4 v[58:61], v[2:3], off
	s_add_i32 s3, 0, 0x12000
	s_add_i32 s21, s21, s33
	v_bfe_u32 v23, v145, 1, 4
	v_bfe_u32 v2, v122, 2, 2
	v_or3_b32 v24, v28, v125, s22
	s_add_u32 s0, s0, s20
	v_or_b32_e32 v31, s3, v30
	v_bitop3_b32 v32, v23, v122, 7 bitop3:0x78
	v_bitop3_b32 v2, v33, v23, v2 bitop3:0x36
	v_lshlrev_b32_e32 v24, 8, v24
	s_addc_u32 s1, s1, 0
	v_lshlrev_b32_e32 v5, 4, v145
	v_or_b32_e32 v3, s22, v1
	v_add3_u32 v130, v31, v29, v24
	v_lshlrev_b32_e32 v24, 8, v122
	v_lshlrev_b32_e32 v25, 4, v32
	v_lshlrev_b32_e32 v2, 4, v2
	s_movk_i32 s23, 0x70
	s_lshl_b64 s[0:1], s[0:1], 9
	v_and_b32_e32 v23, 0x70, v5
	v_add3_u32 v25, 0, v24, v25
	v_add3_u32 v24, s3, v2, v24
	v_lshl_add_u32 v26, v3, 8, 0
	v_bitop3_b32 v5, v124, v5, s23 bitop3:0x78
	s_movk_i32 s23, 0x80
	v_lshl_add_u64 v[2:3], v[118:119], 0, s[0:1]
	v_readlane_b32 s50, v253, 37
	v_readlane_b32 s51, v253, 38
	v_bitop3_b32 v27, v124, v23, 64 bitop3:0x36
	v_bitop3_b32 v28, v124, v23, s23 bitop3:0x36
	v_bitop3_b32 v23, v124, v23, s87 bitop3:0x36
	v_or_b32_e32 v2, v2, v22
	v_mov_b32_e32 v123, 0
	v_or_b32_e32 v140, 0x800, v1
	v_add_u32_e32 v139, 0x7fe, v1
	v_add_u32_e32 v138, 0x7fd, v1
	v_xor_b32_e32 v137, 32, v130
	v_xor_b32_e32 v136, 64, v130
	v_xor_b32_e32 v135, 0x60, v130
	v_xor_b32_e32 v134, 0x80, v130
	v_xor_b32_e32 v133, 0xa0, v130
	v_xor_b32_e32 v132, 0xc0, v130
	v_xor_b32_e32 v131, 0xe0, v130
	v_or_b32_e32 v150, s22, v125
	v_add_u32_e32 v151, s21, v124
	v_lshl_add_u64 v[126:127], s[52:53], 0, v[2:3]
	v_lshl_add_u64 v[128:129], s[54:55], 0, v[2:3]
	v_mov_b32_e32 v147, 0xf149f2ca
	s_mov_b64 s[20:21], 0
	v_add_u32_e32 v148, v25, v30
	v_add_u32_e32 v149, v24, v30
	v_add_u32_e32 v144, v26, v5
	v_add_u32_e32 v143, v26, v27
	v_add_u32_e32 v141, v26, v28
	v_add_u32_e32 v142, v26, v23
	v_mov_b32_e32 v22, 0
	v_mov_b32_e32 v23, v123
	v_mov_b32_e32 v24, v123
	v_mov_b32_e32 v25, v123
	v_mov_b32_e32 v26, 0
	v_mov_b32_e32 v27, v123
	v_mov_b32_e32 v28, v123
	v_mov_b32_e32 v29, v123
	v_mov_b32_e32 v30, 0
	v_mov_b32_e32 v31, v123
	v_mov_b32_e32 v32, v123
	v_mov_b32_e32 v33, v123
	v_mov_b32_e32 v34, 0
	v_mov_b32_e32 v35, v123
	v_mov_b32_e32 v36, v123
	v_mov_b32_e32 v37, v123
	v_mov_b32_e32 v38, 0
	v_mov_b32_e32 v39, v123
	v_mov_b32_e32 v40, v123
	v_mov_b32_e32 v41, v123
	v_mov_b32_e32 v42, 0
	v_mov_b32_e32 v43, v123
	v_mov_b32_e32 v44, v123
	v_mov_b32_e32 v45, v123
	v_mov_b32_e32 v46, 0
	v_mov_b32_e32 v47, v123
	v_mov_b32_e32 v48, v123
	v_mov_b32_e32 v49, v123
	v_mov_b32_e32 v50, 0
	v_mov_b32_e32 v51, v123
	v_mov_b32_e32 v52, v123
	v_mov_b32_e32 v53, v123
	s_mov_b32 s23, 0x140000
	s_mov_b32 s24, 0x160000
	s_mov_b32 s25, 0x100000
	s_mov_b32 s33, 0xff800000
	s_mov_b32 s49, 0x180000
	s_mov_b32 s50, 0x1a0000
	s_mov_b32 s51, 0x1c0000
	s_mov_b32 s52, 0x1e0000
	s_movk_i32 s53, 0x80f
	v_readlane_b32 s56, v253, 43
	v_readlane_b32 s57, v253, 44
	v_readlane_b32 s58, v253, 45
	v_readlane_b32 s59, v253, 46
	v_readlane_b32 s60, v253, 47
	v_readlane_b32 s61, v253, 48
	v_readlane_b32 s62, v253, 49
	v_readlane_b32 s63, v253, 50
.LBB0_643:
	s_waitcnt vmcnt(15)
	v_cvt_pk_bf16_f32 v2, v114, v115
	v_cvt_pk_bf16_f32 v3, v116, v117
	s_waitcnt vmcnt(14)
	v_cvt_pk_bf16_f32 v110, v110, v111
	v_cvt_pk_bf16_f32 v111, v112, v113
	ds_write_b64 v148, v[2:3]
	ds_write_b64 v149, v[110:111]
	s_waitcnt vmcnt(13)
	v_cvt_pk_bf16_f32 v2, v106, v107
	v_cvt_pk_bf16_f32 v3, v108, v109
	s_waitcnt vmcnt(12)
	v_cvt_pk_bf16_f32 v102, v102, v103
	v_cvt_pk_bf16_f32 v103, v104, v105
	ds_write_b64 v148, v[2:3] offset:4096
	ds_write_b64 v149, v[102:103] offset:4096
	s_waitcnt vmcnt(11)
	v_cvt_pk_bf16_f32 v2, v98, v99
	v_cvt_pk_bf16_f32 v3, v100, v101
	s_waitcnt vmcnt(10)
	v_cvt_pk_bf16_f32 v94, v94, v95
	v_cvt_pk_bf16_f32 v95, v96, v97
	ds_write_b64 v148, v[2:3] offset:8192
	ds_write_b64 v149, v[94:95] offset:8192
	s_waitcnt vmcnt(9)
	v_cvt_pk_bf16_f32 v2, v90, v91
	v_cvt_pk_bf16_f32 v3, v92, v93
	s_waitcnt vmcnt(8)
	v_cvt_pk_bf16_f32 v82, v82, v83
	v_cvt_pk_bf16_f32 v83, v84, v85
	ds_write_b64 v148, v[2:3] offset:12288
	ds_write_b64 v149, v[82:83] offset:12288
	s_waitcnt vmcnt(7)
	v_cvt_pk_bf16_f32 v2, v74, v75
	v_cvt_pk_bf16_f32 v3, v76, v77
	s_waitcnt vmcnt(6)
	v_cvt_pk_bf16_f32 v66, v66, v67
	v_cvt_pk_bf16_f32 v67, v68, v69
	ds_write_b64 v148, v[2:3] offset:16384
	ds_write_b64 v149, v[66:67] offset:16384
	s_waitcnt vmcnt(5)
	v_cvt_pk_bf16_f32 v2, v54, v55
	v_cvt_pk_bf16_f32 v3, v56, v57
	s_waitcnt vmcnt(4)
	v_cvt_pk_bf16_f32 v54, v86, v87
	v_cvt_pk_bf16_f32 v55, v88, v89
	ds_write_b64 v148, v[2:3] offset:20480
	ds_write_b64 v149, v[54:55] offset:20480
	s_waitcnt vmcnt(3)
	v_cvt_pk_bf16_f32 v2, v78, v79
	v_cvt_pk_bf16_f32 v3, v80, v81
	s_waitcnt vmcnt(2)
	v_cvt_pk_bf16_f32 v54, v70, v71
	v_cvt_pk_bf16_f32 v55, v72, v73
	ds_write_b64 v148, v[2:3] offset:24576
	ds_write_b64 v149, v[54:55] offset:24576
	s_waitcnt vmcnt(1)
	v_cvt_pk_bf16_f32 v2, v62, v63
	v_cvt_pk_bf16_f32 v3, v64, v65
	s_waitcnt vmcnt(0)
	v_cvt_pk_bf16_f32 v54, v58, v59
	v_cvt_pk_bf16_f32 v55, v60, v61
	ds_write_b64 v148, v[2:3] offset:28672
	ds_write_b64 v149, v[54:55] offset:28672
	v_lshl_add_u64 v[2:3], v[126:127], 0, s[20:21]
	v_add_co_u32_e32 v54, vcc, s25, v2
	v_lshl_add_u64 v[164:165], v[128:129], 0, s[20:21]
	s_nop 0
	v_addc_co_u32_e32 v55, vcc, 0, v3, vcc
	s_waitcnt lgkmcnt(0)
	s_barrier
	global_load_dwordx4 v[114:117], v[54:55], off
	v_add_co_u32_e32 v54, vcc, s25, v164
	ds_read_b128 v[58:61], v144
	s_nop 0
	v_addc_co_u32_e32 v55, vcc, 0, v165, vcc
	global_load_dwordx4 v[110:113], v[54:55], off
	v_add_co_u32_e32 v54, vcc, s47, v2
	ds_read_b128 v[152:155], v141
	ds_read_b128 v[156:159], v142
	v_addc_co_u32_e32 v55, vcc, 0, v3, vcc
	global_load_dwordx4 v[106:109], v[54:55], off
	v_add_co_u32_e32 v54, vcc, s47, v164
	ds_read_b128 v[160:163], v151
	s_nop 0
	v_addc_co_u32_e32 v55, vcc, 0, v165, vcc
	global_load_dwordx4 v[102:105], v[54:55], off
	v_add_co_u32_e32 v54, vcc, s23, v2
	v_cmp_gt_i32_e64 s[0:1], v150, v139
	s_nop 0
	v_addc_co_u32_e32 v55, vcc, 0, v3, vcc
	global_load_dwordx4 v[98:101], v[54:55], off
	v_add_co_u32_e32 v54, vcc, s23, v164
	s_nop 1
	v_addc_co_u32_e32 v55, vcc, 0, v165, vcc
	global_load_dwordx4 v[94:97], v[54:55], off
	v_add_co_u32_e32 v54, vcc, s24, v2
	s_nop 1
	v_addc_co_u32_e32 v55, vcc, 0, v3, vcc
	global_load_dwordx4 v[90:93], v[54:55], off
	v_add_co_u32_e32 v54, vcc, s24, v164
	s_nop 1
	v_addc_co_u32_e32 v55, vcc, 0, v165, vcc
	global_load_dwordx4 v[82:85], v[54:55], off
	v_add_co_u32_e32 v54, vcc, s49, v2
	s_nop 1
	v_addc_co_u32_e32 v55, vcc, 0, v3, vcc
	global_load_dwordx4 v[74:77], v[54:55], off
	v_add_co_u32_e32 v54, vcc, s49, v164
	s_nop 1
	v_addc_co_u32_e32 v55, vcc, 0, v165, vcc
	global_load_dwordx4 v[66:69], v[54:55], off
	v_add_co_u32_e32 v54, vcc, s50, v2
	s_nop 1
	v_addc_co_u32_e32 v55, vcc, 0, v3, vcc
	v_add_co_u32_e32 v62, vcc, s50, v164
	global_load_dwordx4 v[54:57], v[54:55], off
	s_nop 0
	v_addc_co_u32_e32 v63, vcc, 0, v165, vcc
	global_load_dwordx4 v[86:89], v[62:63], off
	ds_read_b128 v[62:65], v143
	v_add_co_u32_e32 v70, vcc, s51, v2
	s_waitcnt lgkmcnt(4)
	v_mfma_f32_16x16x32_bf16 v[58:61], v[58:61], v[18:21], 0
	v_addc_co_u32_e32 v71, vcc, 0, v3, vcc
	global_load_dwordx4 v[78:81], v[70:71], off
	v_add_co_u32_e32 v70, vcc, s51, v164
	s_waitcnt lgkmcnt(0)
	v_mfma_f32_16x16x32_bf16 v[58:61], v[62:65], v[14:17], v[58:61]
	v_addc_co_u32_e32 v71, vcc, 0, v165, vcc
	v_add_co_u32_e32 v2, vcc, s52, v2
	global_load_dwordx4 v[70:73], v[70:71], off
	s_nop 0
	v_addc_co_u32_e32 v3, vcc, 0, v3, vcc
	global_load_dwordx4 v[62:65], v[2:3], off
	v_add_co_u32_e32 v2, vcc, s52, v164
	v_mfma_f32_16x16x32_bf16 v[152:155], v[152:155], v[10:13], v[58:61]
	s_nop 0
	v_addc_co_u32_e32 v3, vcc, 0, v165, vcc
	v_cmp_gt_i32_e32 vcc, v150, v140
	global_load_dwordx4 v[58:61], v[2:3], off
	v_mfma_f32_16x16x32_bf16 v[152:155], v[156:159], v[6:9], v[152:155]
	v_xor_b32_e32 v3, 0x80000000, v163
	v_xor_b32_e32 v2, 0x80000000, v162
	v_mov_b32_e32 v156, v123
	s_nop 4
	v_pk_fma_f32 v[154:155], v[154:155], s[86:87], v[2:3] op_sel_hi:[1,0,1]
	v_pk_fma_f32 v[152:153], v[152:153], s[86:87], v[160:161] op_sel_hi:[1,0,1] neg_lo:[0,0,1] neg_hi:[0,0,1]
	v_mov_b32_e32 v2, s33
	v_cndmask_b32_e32 v3, v154, v154, vcc
	v_cndmask_b32_e32 v5, v155, v155, vcc
	v_cndmask_b32_e32 v2, v152, v2, vcc
	v_cmp_lt_i32_e32 vcc, v150, v140
	s_nop 1
	v_cndmask_b32_e32 v2, v2, v152, vcc
	v_cndmask_b32_e32 v152, v247, v153, vcc
	v_add_u32_e32 v153, 2, v150
	v_cndmask_b32_e32 v5, v5, v155, vcc
	v_cndmask_b32_e32 v3, v3, v154, vcc
	v_cmp_lt_i32_e32 vcc, s53, v153
	s_or_b64 vcc, vcc, s[0:1]
	v_add_u32_e32 v153, 3, v150
	v_cndmask_b32_e32 v3, v3, v247, vcc
	v_cmp_lt_i32_e32 vcc, s53, v153
	v_cmp_gt_i32_e64 s[0:1], v150, v138
	s_or_b64 vcc, vcc, s[0:1]
	v_cndmask_b32_e32 v5, v5, v247, vcc
	v_max_f32_e32 v153, v5, v5
	v_max_f32_e32 v154, v3, v3
	v_max_f32_e32 v153, v154, v153
	v_max3_f32 v153, v2, v152, v153
	ds_swizzle_b32 v154, v153 offset:swizzle(SWAP,16)
	v_mov_b32_e32 v155, v147
	s_waitcnt lgkmcnt(0)
	v_max_f32_e32 v147, v154, v154
	v_max_f32_e32 v147, v153, v147
	v_mov_b32_e32 v153, v147
	s_nop 1
	v_permlane32_swap_b32_e32 v147, v153
	v_max3_f32 v147, v155, v147, v153
	v_sub_f32_e32 v2, v2, v147
	v_exp_f32_e32 v2, v2
	v_sub_f32_e32 v152, v152, v147
	v_exp_f32_e32 v152, v152
	v_sub_f32_e32 v3, v3, v147
	v_exp_f32_e32 v3, v3
	v_sub_f32_e32 v5, v5, v147
	v_exp_f32_e32 v5, v5
	v_add_f32_e32 v153, 0, v2
	v_add_f32_e32 v153, v152, v153
	v_add_f32_e32 v153, v3, v153
	v_add_f32_e32 v153, v5, v153
	ds_swizzle_b32 v154, v153 offset:swizzle(SWAP,16)
	v_sub_f32_e32 v123, v155, v147
	v_exp_f32_e32 v184, v123
	v_cvt_pk_bf16_f32 v2, v2, v152
	v_cvt_pk_bf16_f32 v3, v3, v5
	s_waitcnt lgkmcnt(0)
	v_add_f32_e32 v123, v153, v154
	v_mov_b32_e32 v153, v123
	s_nop 1
	v_permlane32_swap_b32_e32 v123, v153
	v_add_f32_e32 v123, v123, v153
	ds_read_b64_tr_b16 v[152:153], v130 offset:0
	v_fmac_f32_e32 v123, v156, v184
	ds_read_b64_tr_b16 v[156:157], v137 offset:0
	ds_read_b64_tr_b16 v[160:161], v136 offset:0
	ds_read_b64_tr_b16 v[164:165], v135 offset:0
	ds_read_b64_tr_b16 v[168:169], v134 offset:0
	ds_read_b64_tr_b16 v[172:173], v133 offset:0
	ds_read_b64_tr_b16 v[176:177], v132 offset:0
	ds_read_b64_tr_b16 v[180:181], v131 offset:0
	s_waitcnt lgkmcnt(0)
	v_mov_b32_e32 v5, v4
	v_mov_b32_e32 v154, v4
	v_mov_b32_e32 v155, v4
	v_mov_b32_e32 v158, v4
	v_mov_b32_e32 v159, v4
	v_mov_b32_e32 v162, v4
	v_mov_b32_e32 v163, v4
	v_mov_b32_e32 v166, v4
	v_mov_b32_e32 v167, v4
	v_mov_b32_e32 v170, v4
	v_mov_b32_e32 v171, v4
	v_mov_b32_e32 v174, v4
	v_mov_b32_e32 v175, v4
	v_mov_b32_e32 v178, v4
	v_mov_b32_e32 v179, v4
	v_mov_b32_e32 v182, v4
	v_mov_b32_e32 v183, v4
	v_pk_mul_f32 v[52:53], v[52:53], v[184:185] op_sel_hi:[1,0]
	v_pk_mul_f32 v[50:51], v[50:51], v[184:185] op_sel_hi:[1,0]
	v_pk_mul_f32 v[48:49], v[48:49], v[184:185] op_sel_hi:[1,0]
	v_pk_mul_f32 v[46:47], v[46:47], v[184:185] op_sel_hi:[1,0]
	v_pk_mul_f32 v[44:45], v[44:45], v[184:185] op_sel_hi:[1,0]
	v_pk_mul_f32 v[42:43], v[42:43], v[184:185] op_sel_hi:[1,0]
	v_pk_mul_f32 v[40:41], v[40:41], v[184:185] op_sel_hi:[1,0]
	v_pk_mul_f32 v[38:39], v[38:39], v[184:185] op_sel_hi:[1,0]
	v_pk_mul_f32 v[36:37], v[36:37], v[184:185] op_sel_hi:[1,0]
	v_pk_mul_f32 v[34:35], v[34:35], v[184:185] op_sel_hi:[1,0]
	v_pk_mul_f32 v[32:33], v[32:33], v[184:185] op_sel_hi:[1,0]
	v_pk_mul_f32 v[30:31], v[30:31], v[184:185] op_sel_hi:[1,0]
	v_pk_mul_f32 v[28:29], v[28:29], v[184:185] op_sel_hi:[1,0]
	v_pk_mul_f32 v[26:27], v[26:27], v[184:185] op_sel_hi:[1,0]
	v_pk_mul_f32 v[24:25], v[24:25], v[184:185] op_sel_hi:[1,0]
	v_pk_mul_f32 v[22:23], v[22:23], v[184:185] op_sel_hi:[1,0]
	v_mfma_f32_16x16x32_bf16 v[50:53], v[152:155], v[2:5], v[50:53]
	s_add_u32 s20, s20, 0x100000
	s_addc_u32 s21, s21, 0
	v_add_u32_e32 v150, 0x80, v150
	v_mfma_f32_16x16x32_bf16 v[46:49], v[156:159], v[2:5], v[46:49]
	v_add_u32_e32 v151, 0x200, v151
	s_cmp_lg_u32 s20, 0xf00000
	v_mfma_f32_16x16x32_bf16 v[42:45], v[160:163], v[2:5], v[42:45]
	s_barrier
	v_mfma_f32_16x16x32_bf16 v[38:41], v[164:167], v[2:5], v[38:41]
	v_mfma_f32_16x16x32_bf16 v[34:37], v[168:171], v[2:5], v[34:37]
	v_mfma_f32_16x16x32_bf16 v[30:33], v[172:175], v[2:5], v[30:33]
	v_mfma_f32_16x16x32_bf16 v[26:29], v[176:179], v[2:5], v[26:29]
	v_mfma_f32_16x16x32_bf16 v[22:25], v[180:183], v[2:5], v[22:25]
	s_cbranch_scc1 .LBB0_643
	s_waitcnt vmcnt(15)
	v_cvt_pk_bf16_f32 v2, v114, v115
	v_cvt_pk_bf16_f32 v3, v116, v117
	s_waitcnt vmcnt(14)
	v_cvt_pk_bf16_f32 v110, v110, v111
	v_cvt_pk_bf16_f32 v111, v112, v113
	ds_write_b64 v148, v[2:3]
	ds_write_b64 v149, v[110:111]
	s_waitcnt vmcnt(13)
	v_cvt_pk_bf16_f32 v2, v106, v107
	v_cvt_pk_bf16_f32 v3, v108, v109
	s_waitcnt vmcnt(12)
	v_cvt_pk_bf16_f32 v102, v102, v103
	v_cvt_pk_bf16_f32 v103, v104, v105
	ds_write_b64 v148, v[2:3] offset:4096
	ds_write_b64 v149, v[102:103] offset:4096
	s_waitcnt vmcnt(11)
	v_cvt_pk_bf16_f32 v2, v98, v99
	v_cvt_pk_bf16_f32 v3, v100, v101
	s_waitcnt vmcnt(10)
	v_cvt_pk_bf16_f32 v94, v94, v95
	v_cvt_pk_bf16_f32 v95, v96, v97
	ds_write_b64 v148, v[2:3] offset:8192
	ds_write_b64 v149, v[94:95] offset:8192
	s_waitcnt vmcnt(9)
	v_cvt_pk_bf16_f32 v2, v90, v91
	v_cvt_pk_bf16_f32 v3, v92, v93
	s_waitcnt vmcnt(8)
	v_cvt_pk_bf16_f32 v82, v82, v83
	v_cvt_pk_bf16_f32 v83, v84, v85
	ds_write_b64 v148, v[2:3] offset:12288
	ds_write_b64 v149, v[82:83] offset:12288
	s_waitcnt vmcnt(7)
	v_cvt_pk_bf16_f32 v2, v74, v75
	v_cvt_pk_bf16_f32 v3, v76, v77
	s_waitcnt vmcnt(6)
	v_cvt_pk_bf16_f32 v66, v66, v67
	v_cvt_pk_bf16_f32 v67, v68, v69
	ds_write_b64 v148, v[2:3] offset:16384
	ds_write_b64 v149, v[66:67] offset:16384
	s_waitcnt vmcnt(5)
	v_cvt_pk_bf16_f32 v2, v54, v55
	v_cvt_pk_bf16_f32 v3, v56, v57
	s_waitcnt vmcnt(4)
	v_cvt_pk_bf16_f32 v54, v86, v87
	v_cvt_pk_bf16_f32 v55, v88, v89
	ds_write_b64 v148, v[2:3] offset:20480
	ds_write_b64 v149, v[54:55] offset:20480
	s_waitcnt vmcnt(3)
	v_cvt_pk_bf16_f32 v2, v78, v79
	v_cvt_pk_bf16_f32 v3, v80, v81
	s_waitcnt vmcnt(2)
	v_cvt_pk_bf16_f32 v54, v70, v71
	v_cvt_pk_bf16_f32 v55, v72, v73
	ds_write_b64 v148, v[2:3] offset:24576
	ds_write_b64 v149, v[54:55] offset:24576
	s_waitcnt vmcnt(1)
	v_cvt_pk_bf16_f32 v2, v62, v63
	v_cvt_pk_bf16_f32 v3, v64, v65
	s_waitcnt vmcnt(0)
	v_cvt_pk_bf16_f32 v54, v58, v59
	v_cvt_pk_bf16_f32 v55, v60, v61
	ds_write_b64 v148, v[2:3] offset:28672
	ds_write_b64 v149, v[54:55] offset:28672
	s_waitcnt lgkmcnt(0)
	s_barrier
	ds_read_b128 v[54:57], v144
	ds_read_b128 v[58:61], v143
	s_waitcnt lgkmcnt(1)
	v_mfma_f32_16x16x32_bf16 v[54:57], v[54:57], v[18:21], 0
	ds_read_b128 v[62:65], v142
	ds_read_b128 v[66:69], v141
	v_or_b32_e32 v5, s22, v125
	s_lshl_b64 s[0:1], s[18:19], 1
	s_waitcnt lgkmcnt(2)
	v_mfma_f32_16x16x32_bf16 v[54:57], v[58:61], v[14:17], v[54:57]
	s_add_u32 s18, s30, s0
	s_addc_u32 s19, s31, s1
	s_add_u32 s0, s34, s0
	s_waitcnt lgkmcnt(0)
	v_mfma_f32_16x16x32_bf16 v[54:57], v[66:69], v[10:13], v[54:57]
	v_add_u32_e32 v66, 0x780, v5
	v_lshl_add_u32 v2, v66, 2, 0
	v_add_u32_e32 v2, 0x1e000, v2
	ds_read_b128 v[58:61], v2
	v_mfma_f32_16x16x32_bf16 v[54:57], v[62:65], v[6:9], v[54:57]
	s_addc_u32 s1, s35, s1
	s_lshl_b32 s2, s2, 1
	s_add_u32 s18, s18, s2
	s_waitcnt lgkmcnt(0)
	v_xor_b32_e32 v3, 0x80000000, v61
	v_xor_b32_e32 v2, 0x80000000, v60
	s_nop 1
	v_pk_fma_f32 v[56:57], v[56:57], s[86:87], v[2:3] op_sel_hi:[1,0,1]
	v_pk_fma_f32 v[54:55], v[54:55], s[86:87], v[58:59] op_sel_hi:[1,0,1] neg_lo:[0,0,1] neg_hi:[0,0,1]
	v_mov_b32_e32 v2, s33
	v_cmp_gt_i32_e32 vcc, v66, v140
	s_addc_u32 s19, s19, 0
	s_add_u32 s20, s0, s2
	v_cndmask_b32_e32 v3, v56, v56, vcc
	v_cndmask_b32_e32 v58, v57, v57, vcc
	v_cndmask_b32_e32 v2, v54, v2, vcc
	v_cmp_lt_i32_e32 vcc, v66, v140
	s_addc_u32 s21, s1, 0
	v_cmp_gt_i32_e64 s[0:1], v66, v139
	v_cndmask_b32_e32 v3, v3, v56, vcc
	v_add_u32_e32 v56, 0x782, v5
	v_cndmask_b32_e32 v2, v2, v54, vcc
	v_cndmask_b32_e32 v54, v58, v57, vcc
	v_cndmask_b32_e32 v55, v247, v55, vcc
	v_cmp_lt_i32_e32 vcc, s53, v56
	s_or_b64 vcc, vcc, s[0:1]
	v_add_u32_e32 v5, 0x783, v5
	v_cndmask_b32_e32 v3, v3, v247, vcc
	v_cmp_lt_i32_e32 vcc, s53, v5
	v_cmp_gt_i32_e64 s[0:1], v66, v138
	s_or_b64 vcc, vcc, s[0:1]
	v_cndmask_b32_e32 v5, v54, v247, vcc
	v_max_f32_e32 v54, v5, v5
	v_max_f32_e32 v56, v3, v3
	v_max_f32_e32 v54, v56, v54
	v_max3_f32 v54, v2, v55, v54
	ds_swizzle_b32 v56, v54 offset:swizzle(SWAP,16)
	s_mov_b32 s23, 0xff800000
	s_waitcnt lgkmcnt(0)
	v_max_f32_e32 v56, v56, v56
	v_max_f32_e32 v54, v54, v56
	v_mov_b32_e32 v56, v54
	s_nop 1
	v_permlane32_swap_b32_e32 v54, v56
	v_max3_f32 v67, v147, v54, v56
	v_sub_f32_e32 v2, v2, v67
	v_exp_f32_e32 v2, v2
	v_sub_f32_e32 v54, v55, v67
	v_exp_f32_e32 v55, v54
	v_sub_f32_e32 v3, v3, v67
	v_exp_f32_e32 v3, v3
	v_sub_f32_e32 v5, v5, v67
	v_exp_f32_e32 v5, v5
	v_add_f32_e32 v54, 0, v2
	v_add_f32_e32 v54, v55, v54
	v_add_f32_e32 v54, v3, v54
	v_add_f32_e32 v56, v5, v54
	ds_swizzle_b32 v57, v56 offset:swizzle(SWAP,16)
	v_cvt_pk_bf16_f32 v2, v2, v55
	v_cvt_pk_bf16_f32 v3, v3, v5
	v_sub_f32_e32 v58, v147, v67
	v_exp_f32_e32 v62, v58
	s_waitcnt lgkmcnt(0)
	v_add_f32_e32 v63, v56, v57
	ds_read_b64_tr_b16 v[56:57], v130 offset:0
	ds_read_b64_tr_b16 v[68:69], v137 offset:0
	ds_read_b64_tr_b16 v[72:73], v136 offset:0
	ds_read_b64_tr_b16 v[76:77], v135 offset:0
	ds_read_b64_tr_b16 v[80:81], v134 offset:0
	ds_read_b64_tr_b16 v[84:85], v133 offset:0
	ds_read_b64_tr_b16 v[88:89], v132 offset:0
	ds_read_b64_tr_b16 v[92:93], v131 offset:0
	s_waitcnt lgkmcnt(0)
	v_mov_b32_e32 v66, v63
	v_ashrrev_i32_e32 v54, 2, v145
	s_nop 0
	v_permlane32_swap_b32_e32 v63, v66
	v_mov_b32_e32 v5, v4
	v_mov_b32_e32 v58, v4
	v_mov_b32_e32 v59, v4
	v_mov_b32_e32 v70, v4
	v_mov_b32_e32 v71, v4
	v_mov_b32_e32 v74, v4
	v_mov_b32_e32 v75, v4
	v_mov_b32_e32 v78, v4
	v_mov_b32_e32 v79, v4
	v_mov_b32_e32 v82, v4
	v_mov_b32_e32 v83, v4
	v_mov_b32_e32 v86, v4
	v_mov_b32_e32 v87, v4
	v_mov_b32_e32 v90, v4
	v_mov_b32_e32 v91, v4
	v_mov_b32_e32 v94, v4
	v_mov_b32_e32 v95, v4
	v_pk_mul_f32 v[52:53], v[52:53], v[62:63] op_sel_hi:[1,0]
	v_pk_mul_f32 v[50:51], v[50:51], v[62:63] op_sel_hi:[1,0]
	v_pk_mul_f32 v[48:49], v[48:49], v[62:63] op_sel_hi:[1,0]
	v_pk_mul_f32 v[46:47], v[46:47], v[62:63] op_sel_hi:[1,0]
	v_pk_mul_f32 v[44:45], v[44:45], v[62:63] op_sel_hi:[1,0]
	v_pk_mul_f32 v[42:43], v[42:43], v[62:63] op_sel_hi:[1,0]
	v_pk_mul_f32 v[40:41], v[40:41], v[62:63] op_sel_hi:[1,0]
	v_pk_mul_f32 v[38:39], v[38:39], v[62:63] op_sel_hi:[1,0]
	v_pk_mul_f32 v[36:37], v[36:37], v[62:63] op_sel_hi:[1,0]
	v_pk_mul_f32 v[34:35], v[34:35], v[62:63] op_sel_hi:[1,0]
	v_pk_mul_f32 v[32:33], v[32:33], v[62:63] op_sel_hi:[1,0]
	v_pk_mul_f32 v[30:31], v[30:31], v[62:63] op_sel_hi:[1,0]
	v_pk_mul_f32 v[28:29], v[28:29], v[62:63] op_sel_hi:[1,0]
	v_pk_mul_f32 v[26:27], v[26:27], v[62:63] op_sel_hi:[1,0]
	v_pk_mul_f32 v[24:25], v[24:25], v[62:63] op_sel_hi:[1,0]
	v_pk_mul_f32 v[22:23], v[22:23], v[62:63] op_sel_hi:[1,0]
	v_mfma_f32_16x16x32_bf16 v[50:53], v[56:59], v[2:5], v[50:53]
	v_lshrrev_b32_e32 v55, 2, v54
	v_cmp_lt_i32_e32 vcc, 15, v54
	v_mfma_f32_16x16x32_bf16 v[46:49], v[68:71], v[2:5], v[46:49]
	v_and_b32_e32 v71, 7, v54
	v_and_or_b32 v69, v55, 3, v146
	s_barrier
	v_mfma_f32_16x16x32_bf16 v[42:45], v[72:75], v[2:5], v[42:45]
	v_mfma_f32_16x16x32_bf16 v[38:41], v[76:79], v[2:5], v[38:41]
	v_mfma_f32_16x16x32_bf16 v[34:37], v[80:83], v[2:5], v[34:37]
	v_mfma_f32_16x16x32_bf16 v[30:33], v[84:87], v[2:5], v[30:33]
	v_mfma_f32_16x16x32_bf16 v[26:29], v[88:91], v[2:5], v[26:29]
	v_mfma_f32_16x16x32_bf16 v[22:25], v[92:95], v[2:5], v[22:25]
	v_and_b32_e32 v2, 3, v145
	v_lshlrev_b32_e32 v3, 8, v54
	v_lshlrev_b32_e32 v5, 2, v2
	v_add_u32_e32 v68, 0, v3
	v_add_u32_e32 v70, s3, v3
	v_xor_b32_e32 v3, v5, v71
	v_xor_b32_e32 v55, v69, v5
	v_lshl_add_u32 v72, v3, 4, v68
	v_lshl_add_u32 v73, v55, 4, v70
	s_and_saveexec_b64 s[0:1], vcc
	s_xor_b64 s[0:1], exec, s[0:1]
	s_movk_i32 s33, 0x80f
	s_cbranch_execz .LBB0_646
	v_readlane_b32 s24, v254, 28
	v_readlane_b32 s25, v254, 29
	s_mov_b32 s50, s25
	s_mov_b32 s51, s25
	s_mov_b32 s48, s25
	s_mov_b32 s49, s25
	v_mov_b64_e32 v[58:59], s[50:51]
	v_mov_b64_e32 v[56:57], s[48:49]
	s_mov_b32 s48, 0xc0000
	ds_write_b128 v72, v[56:59]
	ds_write_b128 v73, v[56:59]
